# phase-4 SwiGLU+LN-fold epilogue: packed f32 ops split into scalar f32 ops (same rounding) so that 91 of 142 register-shuffle moves per wave fold away by copy propagation
# speedup vs baseline: 1.0043x; 1.0043x over previous
; __device__ __forceinline__ u32x4 pack8bf(const f32x4 a, const f32x4 b) { u32x4 w; w.x = cvt_pk_bf16(a[0], a[1]); w.y = cvt_pk_bf16(a[2], a[3]); w.z = cvt_pk_bf16(b[0], b[1]); w.w = cvt_pk_bf16(b[2], b[3]); return w; }
;     ...
;         if constexpr (QM == 2) { const float qs0_ = g.qs * E.qscale(cur), qs1_ = qs0_ * g.qs_b1; _Pragma("unroll") for (int a = 0; a < 2; ++a) _Pragma("unroll") for (int b = 0; b < 2; ++b) _Pragma("unroll") for (int m = 0; m < 4; ++m) _Pragma("unroll") for (int n = 0; n < 2; ++n) { const v4i t_ = __builtin_bit_cast(v4i, acc[a][b][m][n]); acc[a][b][m][n] = (f32x4){(float)t_[0], (float)t_[1], (float)t_[2], (float)t_[3]} * (b == 0 ? qs0_ : qs1_); } }
;     __device__ __forceinline__ void operator()(EPI_ARGS) const {
;         const int row0 = u.pm * BM + wr * 64 + fr, col0 = u.pn * HALF + wc * 32 + 8 * fq, n0 = u.pn * BM + wc * 32 + 8 * fq;
;         f32x4 cg[2], dg[2], cu[2], du[2];
;         if constexpr (FOLD) {
; #pragma unroll
;             for (int n = 0; n < 2; ++n) { cg[n] = *(const f32x4*)(C + n0 + 4 * n); dg[n] = *(const f32x4*)(D + n0 + 4 * n); cu[n] = *(const f32x4*)(C + n0 + HALF + 4 * n); du[n] = *(const f32x4*)(D + n0 + HALF + 4 * n);
;                 if constexpr (PRE) { float os_ = oscale; asm volatile("" : "+s"(os_)); cu[n] = cu[n] * os_; du[n] = du[n] * os_; } } }
; #pragma unroll
;         for (int ai = 0; ai < 2; ++ai)
; #pragma unroll
;             for (int m = 0; m < 4; ++m) { const int row = row0 + ai * HALF + m * 16; f32x4 r[2];
;                 float mu = 0.f, rs = 1.f; if constexpr (FOLD) ln_stats(st, row, mu, rs);
; #pragma unroll
;                 for (int n = 0; n < 2; ++n) { f32x4 g = acc[ai][0][m][n], up = acc[ai][1][m][n];
;                     if constexpr (!PRE) { g = g * ascale; up = up * ascale; }
;                     if constexpr (FOLD) { g = (g - cg[n] * mu) * rs + dg[n]; up = (up - cu[n] * mu) * rs + du[n]; }
;                     if constexpr (!PRE) up = up * oscale;
; #pragma unroll
;                     for (int j = 0; j < 4; ++j) { const float e = __builtin_amdgcn_exp2f(g[j] * -1.4426950408889634f); r[n][j] = g[j] * __builtin_amdgcn_rcpf(1.0f + e) * up[j]; } }
;                 if constexpr (F8OUT) *(u32x2*)((unsigned char*)O + (size_t)row * ldc + col0) = pack8fp8(r[0], r[1]);
;                 else *(u32x4*)((bf16_t*)O + (size_t)row * ldc + col0) = pack8bf(r[0], r[1]); }
.LBB0_3779:
	v_lshl_or_b32 v84, s5, 8, v168
	v_lshl_add_u32 v160, s4, 8, v166
	v_ashrrev_i32_e32 v85, 31, v84
	v_lshlrev_b64 v[84:85], 2, v[84:85]
	v_ashrrev_i32_e32 v161, 31, v160
	v_lshl_add_u64 v[88:89], s[8:9], 0, v[84:85]
	v_lshl_add_u64 v[182:183], s[10:11], 0, v[84:85]
	s_mov_b32 s4, 0x41800000
	s_mov_b32 s40, 0x41800000
	v_lshl_add_u64 v[186:187], v[160:161], 3, s[14:15]
	global_load_dwordx4 v[96:99], v[88:89], off
	global_load_dwordx4 v[162:165], v[88:89], off offset:512
	global_load_dwordx4 v[100:103], v[182:183], off
	global_load_dwordx4 v[174:177], v[182:183], off offset:512
	global_load_dwordx4 v[84:87], v[88:89], off offset:16
	global_load_dwordx4 v[178:181], v[88:89], off offset:528
	s_nop 0
	global_load_dwordx4 v[88:91], v[182:183], off offset:16
	s_nop 0
	global_load_dwordx4 v[182:185], v[182:183], off offset:528
	global_load_dwordx2 v[226:227], v[186:187], off offset:128
	global_load_dwordx2 v[228:229], v[186:187], off offset:256
	global_load_dwordx2 v[230:231], v[186:187], off offset:384
	global_load_dwordx2 v[232:233], v[186:187], off offset:1024
	global_load_dwordx2 v[234:235], v[186:187], off offset:1152
	global_load_dwordx2 v[236:237], v[186:187], off offset:1280
	global_load_dwordx2 v[238:239], v[186:187], off offset:1408
	global_load_dwordx2 v[186:187], v[186:187], off
	v_cvt_f32_i32_e32 v131, v131
	v_cvt_f32_i32_e32 v130, v130
	v_cvt_f32_i32_e32 v137, v137
	v_cvt_f32_i32_e32 v136, v136
	v_cvt_f32_i32_e32 v141, v141
	v_mul_f32_e32 v194, s24, v130
	v_mul_f32_e32 v195, s24, v131
	v_cvt_f32_i32_e32 v140, v140
	v_cvt_f32_i32_e32 v133, v133
	v_cvt_f32_i32_e32 v132, v132
	v_mul_f32_e32 v192, s20, v136
	v_mul_f32_e32 v193, s20, v137
	v_cvt_f32_i32_e32 v139, v139
	v_cvt_f32_i32_e32 v138, v138
	v_cvt_f32_i32_e32 v135, v135
	v_cvt_f32_i32_e32 v134, v134
	v_mul_f32_e32 v140, s20, v140
	v_mul_f32_e32 v141, s20, v141
	v_mul_f32_e32 v132, s24, v132
	v_mul_f32_e32 v133, s24, v133
	v_mul_f32_e32 v190, s20, v138
	v_mul_f32_e32 v191, s20, v139
	v_mul_f32_e32 v134, s24, v134
	v_mul_f32_e32 v135, s24, v135
	v_mov_b32_e32 v138, v132
	v_mov_b32_e32 v139, v140
	v_mov_b32_e32 v140, v133
	v_cvt_f32_i32_e32 v188, v128
	v_lshl_or_b32 v128, s5, 7, v168
	v_mov_b32_e32 v196, v134
	v_cvt_f32_i32_e32 v143, v143
	v_cvt_f32_i32_e32 v142, v142
	v_cvt_f32_i32_e32 v189, v129
	v_ashrrev_i32_e32 v129, 31, v128
	v_cvt_f32_i32_e32 v125, v125
	v_mul_f32_e32 v142, s20, v142
	v_mul_f32_e32 v143, s20, v143
	v_mul_f32_e32 v188, s24, v188
	v_mul_f32_e32 v189, s24, v189
	v_mov_b32_e32 v197, v142
	v_mov_b32_e32 v142, v135
	v_cvt_f32_i32_e32 v124, v124
	v_cvt_f32_i32_e32 v117, v117
	v_cvt_f32_i32_e32 v116, v116
	v_cvt_f32_i32_e32 v127, v127
	v_mul_f32_e32 v124, s20, v124
	v_mul_f32_e32 v125, s20, v125
	v_cvt_f32_i32_e32 v126, v126
	v_mul_f32_e32 v116, s24, v116
	v_mul_f32_e32 v117, s24, v117
	v_cvt_f32_i32_e32 v119, v119
	v_cvt_f32_i32_e32 v118, v118
	v_mul_f32_e32 v126, s20, v126
	v_mul_f32_e32 v127, s20, v127
	v_cvt_f32_i32_e32 v121, v121
	v_cvt_f32_i32_e32 v120, v120
	v_mul_f32_e32 v118, s24, v118
	v_mul_f32_e32 v119, s24, v119
	v_cvt_f32_i32_e32 v113, v113
	v_cvt_f32_i32_e32 v112, v112
	v_mul_f32_e32 v120, s20, v120
	v_mul_f32_e32 v121, s20, v121
	v_cvt_f32_i32_e32 v123, v123
	v_cvt_f32_i32_e32 v122, v122
	v_mul_f32_e32 v112, s24, v112
	v_mul_f32_e32 v113, s24, v113
	v_cvt_f32_i32_e32 v115, v115
	v_cvt_f32_i32_e32 v114, v114
	v_mul_f32_e32 v122, s20, v122
	v_mul_f32_e32 v123, s20, v123
	v_cvt_f32_i32_e32 v109, v109
	v_cvt_f32_i32_e32 v108, v108
	v_mul_f32_e32 v114, s24, v114
	v_mul_f32_e32 v115, s24, v115
	v_cvt_f32_i32_e32 v93, v93
	v_cvt_f32_i32_e32 v92, v92
	v_mul_f32_e32 v108, s20, v108
	v_mul_f32_e32 v109, s20, v109
	v_cvt_f32_i32_e32 v111, v111
	v_cvt_f32_i32_e32 v110, v110
	v_mul_f32_e32 v92, s24, v92
	v_mul_f32_e32 v93, s24, v93
	v_cvt_f32_i32_e32 v95, v95
	v_cvt_f32_i32_e32 v94, v94
	v_mul_f32_e32 v110, s20, v110
	v_mul_f32_e32 v111, s20, v111
	v_cvt_f32_i32_e32 v105, v105
	v_cvt_f32_i32_e32 v104, v104
	v_mul_f32_e32 v94, s24, v94
	v_mul_f32_e32 v95, s24, v95
	v_cvt_f32_i32_e32 v81, v81
	v_cvt_f32_i32_e32 v80, v80
	s_waitcnt vmcnt(0)
	v_mov_b32_e32 v137, v96
	v_mul_f32_e32 v162, s4, v162
	v_mul_f32_e32 v163, s4, v163
	v_mov_b32_e32 v131, v102
	v_mov_b32_e32 v136, v162
	v_mul_f32_e32 v164, s4, v164
	v_mul_f32_e32 v165, s4, v165
	v_mov_b32_e32 v96, v163
	v_mul_f32_e32 v174, s4, v174
	v_mul_f32_e32 v175, s4, v175
	v_mul_f32_e32 v186, s26, v186
	v_mul_f32_e32 v187, s26, v187
	v_mov_b32_e32 v133, v98
	v_fma_f32 v102, -v186, v186, v187
	v_add_f32_e32 v102, 0x3727c5ac, v102
	v_rsq_f32_e32 v242, v102
	v_mov_b32_e32 v132, v164
	v_mov_b32_e32 v98, v165
	v_mul_f32_e32 v176, s4, v176
	v_mul_f32_e32 v177, s4, v177
	v_mov_b32_e32 v134, v174
	v_mov_b32_e32 v135, v100
	v_mov_b32_e32 v100, v175
	v_mov_b32_e32 v130, v176
	v_fma_f32 v138, -v136, v186, v138
	v_fma_f32 v139, -v137, v186, v139
	v_fma_f32 v140, -v96, v186, v140
	v_fma_f32 v141, -v97, v186, v141
	v_mov_b32_e32 v102, v177
	v_fma_f32 v142, -v98, v186, v142
	v_fma_f32 v143, -v99, v186, v143
	v_fma_f32 v162, -v132, v186, v196
	v_fma_f32 v163, -v133, v186, v197
	v_fma_f32 v138,v138,v242,v134
	v_fma_f32 v139,v139,v242,v135
	v_fma_f32 v140,v140,v242,v100
	v_fma_f32 v141,v141,v242,v101
	v_mul_f32_e32 v161, 0xbfb8aa3b, v139
	v_mul_f32_e32 v165, 0xbfb8aa3b, v141
	v_exp_f32_e32 v161, v161
	v_exp_f32_e32 v165, v165
	v_mul_f32_e32 v178, s40, v178
	v_mul_f32_e32 v179, s40, v179
	v_mul_f32_e32 v182, s40, v182
	v_mul_f32_e32 v183, s40, v183
	v_add_f32_e32 v161, 1.0, v161
	v_fma_f32 v162,v162,v242,v130
	v_fma_f32 v163,v163,v242,v131
	v_add_f32_e32 v165, 1.0, v165
	v_rcp_f32_e32 v161, v161
	v_rcp_f32_e32 v165, v165
; __device__ __forceinline__ u32x4 pack8bf(const f32x4 a, const f32x4 b) { u32x4 w; w.x = cvt_pk_bf16(a[0], a[1]); w.y = cvt_pk_bf16(a[2], a[3]); w.z = cvt_pk_bf16(b[0], b[1]); w.w = cvt_pk_bf16(b[2], b[3]); return w; }
;     __device__ __forceinline__ float qscale(const Unit& u) const { return ((u.pn >= 8 && u.pn <= 11) || u.pn == 17) ? 0.5f : 1.0f; }
; __device__ __forceinline__ void ln_stats(const float* st, int row, float& mu, float& rs) { const f32x2 s = *(const f32x2*)(st + 2 * (size_t)row); mu = s[0] * (1.0f / DM); rs = 1.0f / sqrtf(s[1] * (1.0f / DM) - mu * mu + LN_EPS); }
;     ...
;         if constexpr (QM == 2) { const float qs0_ = g.qs * E.qscale(cur), qs1_ = qs0_ * g.qs_b1; _Pragma("unroll") for (int a = 0; a < 2; ++a) _Pragma("unroll") for (int b = 0; b < 2; ++b) _Pragma("unroll") for (int m = 0; m < 4; ++m) _Pragma("unroll") for (int n = 0; n < 2; ++n) { const v4i t_ = __builtin_bit_cast(v4i, acc[a][b][m][n]); acc[a][b][m][n] = (f32x4){(float)t_[0], (float)t_[1], (float)t_[2], (float)t_[3]} * (b == 0 ? qs0_ : qs1_); } }
;     __device__ __forceinline__ void operator()(EPI_ARGS) const {
;     ...
;         for (int ai = 0; ai < 2; ++ai)
; #pragma unroll
;             for (int m = 0; m < 4; ++m) { const int row = row0 + ai * HALF + m * 16; f32x4 r[2];
;                 float mu = 0.f, rs = 1.f; if constexpr (FOLD) ln_stats(st, row, mu, rs);
; #pragma unroll
;                 for (int n = 0; n < 2; ++n) { f32x4 g = acc[ai][0][m][n], up = acc[ai][1][m][n];
;                     if constexpr (!PRE) { g = g * ascale; up = up * ascale; }
;                     if constexpr (FOLD) { g = (g - cg[n] * mu) * rs + dg[n]; up = (up - cu[n] * mu) * rs + du[n]; }
;                     if constexpr (!PRE) up = up * oscale;
; #pragma unroll
;                     for (int j = 0; j < 4; ++j) { const float e = __builtin_amdgcn_exp2f(g[j] * -1.4426950408889634f); r[n][j] = g[j] * __builtin_amdgcn_rcpf(1.0f + e) * up[j]; } }
;                 if constexpr (F8OUT) *(u32x2*)((unsigned char*)O + (size_t)row * ldc + col0) = pack8fp8(r[0], r[1]);
;                 else *(u32x4*)((bf16_t*)O + (size_t)row * ldc + col0) = pack8bf(r[0], r[1]); }
	v_mul_f32_e32 v174, 0xbfb8aa3b, v163
	v_exp_f32_e32 v174, v174
	v_mul_f32_e32 v139, v139, v161
	v_fma_f32 v142,v142,v242,v102
	v_fma_f32 v143,v143,v242,v103
	v_mul_f32_e32 v161, v138, v139
	v_mul_f32_e32 v138, 0xbfb8aa3b, v143
	v_exp_f32_e32 v138, v138
	v_add_f32_e32 v139, 1.0, v174
	v_mul_f32_e32 v141, v141, v165
	v_rcp_f32_e32 v165, v139
	v_add_f32_e32 v138, 1.0, v138
	v_mul_f32_e32 v196, v140, v141
	v_rcp_f32_e32 v176, v138
	v_mov_b32_e32 v138, v178
	v_mov_b32_e32 v139, v84
	v_fma_f32 v174,-v186,v138,v188
	v_fma_f32 v175,-v186,v139,v192
	v_mov_b32_e32 v140, v182
	v_mov_b32_e32 v141, v88
	v_fma_f32 v174,v174,v242,v140
	v_fma_f32 v175,v175,v242,v141
	v_mul_f32_e32 v88, v163, v165
	v_mul_f32_e32 v84, 0xbfb8aa3b, v175
	v_exp_f32_e32 v84, v84
	v_mov_b32_e32 v192, v189
	v_mul_f32_e32 v182, v162, v88
	v_mov_b32_e32 v88, v183
	v_add_f32_e32 v84, 1.0, v84
	v_rcp_f32_e32 v165, v84
	v_mov_b32_e32 v84, v179
	v_fma_f32 v162, -v186, v84, v192
	v_fma_f32 v163, -v186, v85, v193
	v_mul_f32_e32 v143, v143, v176
	v_fma_f32 v176,v162,v242,v88
	v_fma_f32 v177,v163,v242,v89
	v_mul_f32_e32 v183, v142, v143
	v_mul_f32_e32 v162, 0xbfb8aa3b, v177
	v_exp_f32_e32 v162, v162
	v_mul_f32_e32 v142, v175, v165
	v_mul_f32_e32 v180, s40, v180
	v_mul_f32_e32 v181, s40, v181
	v_mul_f32_e32 v188, v174, v142
	v_add_f32_e32 v142, 1.0, v162
	v_mul_f32_e32 v184, s40, v184
	v_mul_f32_e32 v185, s40, v185
	v_rcp_f32_e32 v189, v142
	v_mov_b32_e32 v142, v180
	v_mov_b32_e32 v143, v86
	v_fma_f32 v174,-v186,v142,v194
	v_fma_f32 v175,-v186,v143,v190
	v_mov_b32_e32 v162, v184
	v_mov_b32_e32 v163, v90
	v_fma_f32 v174,v174,v242,v162
	v_fma_f32 v175,v175,v242,v163
	v_mov_b32_e32 v190, v195
	v_mul_f32_e32 v86, 0xbfb8aa3b, v175
	v_exp_f32_e32 v180, v86
	v_mov_b32_e32 v86, v181
	v_fma_f32 v178, -v186, v86, v190
	v_fma_f32 v179, -v186, v87, v191
	v_mov_b32_e32 v90, v185
	v_fma_f32 v165,v179,v242,v91
	v_fma_f32 v164,v178,v242,v90
	v_add_f32_e32 v179, 1.0, v180
	v_mul_f32_e32 v178, 0xbfb8aa3b, v165
	v_exp_f32_e32 v178, v178
	v_rcp_f32_e32 v179, v179
	v_mul_f32_e32 v177, v177, v189
	v_mul_f32_e32 v176, v176, v177
	v_add_f32_e32 v178, 1.0, v178
	v_rcp_f32_e32 v178, v178
	v_mul_f32_e32 v175, v175, v179
	v_mul_f32_e32 v177, v174, v175
	v_med3_f32 v161, v161, s62, v173
	v_mul_f32_e32 v165, v165, v178
	v_mul_f32_e32 v164, v164, v165
	v_med3_f32 v165, v196, s62, v173
	v_cvt_pk_fp8_f32 v174, v161, v165
	v_med3_f32 v178, v188, s62, v173
	v_med3_f32 v176, v176, s62, v173
	v_cvt_pk_fp8_f32 v175, v178, v176
	v_med3_f32 v161, v182, s62, v173
	v_med3_f32 v165, v183, s62, v173
	v_cvt_pk_fp8_f32 v174, v161, v165 op_sel:[0,0,1]
	v_med3_f32 v161, v177, s62, v173
	v_med3_f32 v164, v164, s62, v173
	v_cvt_pk_fp8_f32 v175, v161, v164 op_sel:[0,0,1]
	v_mov_b64_e32 v[164:165], s[12:13]
	v_mad_i64_i32 v[176:177], s[4:5], v160, s63, v[164:165]
	v_lshl_add_u64 v[176:177], v[176:177], 0, v[128:129]
	global_store_dwordx2 v[176:177], v[174:175], off
	v_or_b32_e32 v174, 16, v160
	v_ashrrev_i32_e32 v175, 31, v174
	v_lshl_add_u64 v[176:177], v[174:175], 3, s[14:15]
	v_mul_f32_e32 v104, s20, v104
	v_mul_f32_e32 v105, s20, v105
	v_mul_f32_e32 v80, s24, v80
	v_mul_f32_e32 v81, s24, v81
	v_cvt_f32_i32_e32 v107, v107
	v_cvt_f32_i32_e32 v106, v106
	v_cvt_f32_i32_e32 v83, v83
	v_cvt_f32_i32_e32 v82, v82
	v_cvt_f32_i32_e32 v77, v77
	v_mul_f32_e32 v106, s20, v106
	v_mul_f32_e32 v107, s20, v107
	v_cvt_f32_i32_e32 v76, v76
	v_mul_f32_e32 v82, s24, v82
	v_mul_f32_e32 v83, s24, v83
	v_cvt_f32_i32_e32 v69, v69
	v_cvt_f32_i32_e32 v68, v68
	v_mul_f32_e32 v76, s20, v76
	v_mul_f32_e32 v77, s20, v77
	v_cvt_f32_i32_e32 v79, v79
	v_cvt_f32_i32_e32 v78, v78
	v_mul_f32_e32 v68, s24, v68
	v_mul_f32_e32 v69, s24, v69
	v_cvt_f32_i32_e32 v71, v71
	v_cvt_f32_i32_e32 v70, v70
	v_mul_f32_e32 v78, s20, v78
	v_mul_f32_e32 v79, s20, v79
	v_cvt_f32_i32_e32 v73, v73
	v_cvt_f32_i32_e32 v72, v72
	v_mul_f32_e32 v70, s24, v70
	v_mul_f32_e32 v71, s24, v71
	v_cvt_f32_i32_e32 v65, v65
	v_cvt_f32_i32_e32 v64, v64
	v_mul_f32_e32 v72, s20, v72
	v_mul_f32_e32 v73, s20, v73
	v_cvt_f32_i32_e32 v75, v75
	v_cvt_f32_i32_e32 v74, v74
	v_mul_f32_e32 v64, s24, v64
	v_mul_f32_e32 v65, s24, v65
	v_cvt_f32_i32_e32 v67, v67
	v_cvt_f32_i32_e32 v66, v66
	v_mul_f32_e32 v74, s20, v74
	v_mul_f32_e32 v75, s20, v75
	v_cvt_f32_i32_e32 v61, v61
	v_cvt_f32_i32_e32 v60, v60
	v_mul_f32_e32 v66, s24, v66
	v_mul_f32_e32 v67, s24, v67
	v_cvt_f32_i32_e32 v53, v53
	v_cvt_f32_i32_e32 v52, v52
	v_mul_f32_e32 v60, s20, v60
	v_mul_f32_e32 v61, s20, v61
	v_cvt_f32_i32_e32 v63, v63
	v_cvt_f32_i32_e32 v62, v62
	v_mul_f32_e32 v52, s24, v52
	v_mul_f32_e32 v53, s24, v53
	v_cvt_f32_i32_e32 v55, v55
	v_cvt_f32_i32_e32 v54, v54
	v_mul_f32_e32 v62, s20, v62
	v_mul_f32_e32 v63, s20, v63
	v_cvt_f32_i32_e32 v57, v57
	v_cvt_f32_i32_e32 v56, v56
	v_mul_f32_e32 v54, s24, v54
	v_mul_f32_e32 v55, s24, v55
	v_cvt_f32_i32_e32 v49, v49
	v_cvt_f32_i32_e32 v48, v48
	v_mul_f32_e32 v56, s20, v56
	v_mul_f32_e32 v57, s20, v57
	v_cvt_f32_i32_e32 v59, v59
	v_cvt_f32_i32_e32 v58, v58
	v_mul_f32_e32 v48, s24, v48
	v_mul_f32_e32 v49, s24, v49
	v_cvt_f32_i32_e32 v51, v51
	v_cvt_f32_i32_e32 v50, v50
	v_mul_f32_e32 v58, s20, v58
	v_mul_f32_e32 v59, s20, v59
	v_cvt_f32_i32_e32 v45, v45
	v_cvt_f32_i32_e32 v44, v44
	v_mul_f32_e32 v50, s24, v50
	v_mul_f32_e32 v51, s24, v51
	v_cvt_f32_i32_e32 v37, v37
	v_cvt_f32_i32_e32 v36, v36
	v_mul_f32_e32 v44, s20, v44
	v_mul_f32_e32 v45, s20, v45
	v_cvt_f32_i32_e32 v47, v47
	v_cvt_f32_i32_e32 v46, v46
	v_mul_f32_e32 v36, s24, v36
	v_mul_f32_e32 v37, s24, v37
	v_cvt_f32_i32_e32 v39, v39
	v_cvt_f32_i32_e32 v38, v38
	v_mul_f32_e32 v46, s20, v46
	v_mul_f32_e32 v47, s20, v47
	v_cvt_f32_i32_e32 v41, v41
; __device__ __forceinline__ u32x4 pack8bf(const f32x4 a, const f32x4 b) { u32x4 w; w.x = cvt_pk_bf16(a[0], a[1]); w.y = cvt_pk_bf16(a[2], a[3]); w.z = cvt_pk_bf16(b[0], b[1]); w.w = cvt_pk_bf16(b[2], b[3]); return w; }
;     __device__ __forceinline__ float qscale(const Unit& u) const { return ((u.pn >= 8 && u.pn <= 11) || u.pn == 17) ? 0.5f : 1.0f; }
; __device__ __forceinline__ void ln_stats(const float* st, int row, float& mu, float& rs) { const f32x2 s = *(const f32x2*)(st + 2 * (size_t)row); mu = s[0] * (1.0f / DM); rs = 1.0f / sqrtf(s[1] * (1.0f / DM) - mu * mu + LN_EPS); }
;     ...
;         if constexpr (QM == 2) { const float qs0_ = g.qs * E.qscale(cur), qs1_ = qs0_ * g.qs_b1; _Pragma("unroll") for (int a = 0; a < 2; ++a) _Pragma("unroll") for (int b = 0; b < 2; ++b) _Pragma("unroll") for (int m = 0; m < 4; ++m) _Pragma("unroll") for (int n = 0; n < 2; ++n) { const v4i t_ = __builtin_bit_cast(v4i, acc[a][b][m][n]); acc[a][b][m][n] = (f32x4){(float)t_[0], (float)t_[1], (float)t_[2], (float)t_[3]} * (b == 0 ? qs0_ : qs1_); } }
;     __device__ __forceinline__ void operator()(EPI_ARGS) const {
;     ...
;         for (int ai = 0; ai < 2; ++ai)
; #pragma unroll
;             for (int m = 0; m < 4; ++m) { const int row = row0 + ai * HALF + m * 16; f32x4 r[2];
;                 float mu = 0.f, rs = 1.f; if constexpr (FOLD) ln_stats(st, row, mu, rs);
; #pragma unroll
;                 for (int n = 0; n < 2; ++n) { f32x4 g = acc[ai][0][m][n], up = acc[ai][1][m][n];
;                     if constexpr (!PRE) { g = g * ascale; up = up * ascale; }
;                     if constexpr (FOLD) { g = (g - cg[n] * mu) * rs + dg[n]; up = (up - cu[n] * mu) * rs + du[n]; }
;                     if constexpr (!PRE) up = up * oscale;
; #pragma unroll
;                     for (int j = 0; j < 4; ++j) { const float e = __builtin_amdgcn_exp2f(g[j] * -1.4426950408889634f); r[n][j] = g[j] * __builtin_amdgcn_rcpf(1.0f + e) * up[j]; } }
;                 if constexpr (F8OUT) *(u32x2*)((unsigned char*)O + (size_t)row * ldc + col0) = pack8fp8(r[0], r[1]);
;                 else *(u32x4*)((bf16_t*)O + (size_t)row * ldc + col0) = pack8bf(r[0], r[1]); }
	v_cvt_f32_i32_e32 v40, v40
	v_mul_f32_e32 v38, s24, v38
	v_mul_f32_e32 v39, s24, v39
	v_cvt_f32_i32_e32 v33, v33
	v_cvt_f32_i32_e32 v32, v32
	v_mul_f32_e32 v40, s20, v40
	v_mul_f32_e32 v41, s20, v41
	v_cvt_f32_i32_e32 v43, v43
	v_cvt_f32_i32_e32 v42, v42
	v_mul_f32_e32 v32, s24, v32
	v_mul_f32_e32 v33, s24, v33
	v_cvt_f32_i32_e32 v35, v35
	v_cvt_f32_i32_e32 v34, v34
	v_mul_f32_e32 v42, s20, v42
	v_mul_f32_e32 v43, s20, v43
	v_mul_f32_e32 v176,s26,v226
	v_mul_f32_e32 v177,s26,v227
	v_cvt_f32_i32_e32 v29, v29
	v_fma_f32 v161, -v176, v176, v177
	v_add_f32_e32 v161, 0x3727c5ac, v161
	v_rsq_f32_e32 v242, v161
	v_mul_f32_e32 v34, s24, v34
	v_mul_f32_e32 v35, s24, v35
	v_cvt_f32_i32_e32 v28, v28
	v_cvt_f32_i32_e32 v21, v21
	v_cvt_f32_i32_e32 v20, v20
	v_mul_f32_e32 v28, s20, v28
	v_mul_f32_e32 v29, s20, v29
	v_mul_f32_e32 v20, s24, v20
	v_mul_f32_e32 v21, s24, v21
	v_cvt_f32_i32_e32 v31, v31
	v_cvt_f32_i32_e32 v30, v30
	v_cvt_f32_i32_e32 v23, v23
	v_cvt_f32_i32_e32 v22, v22
	v_mul_f32_e32 v30, s20, v30
	v_mul_f32_e32 v31, s20, v31
	v_mul_f32_e32 v22, s24, v22
	v_mul_f32_e32 v23, s24, v23
	v_cvt_f32_i32_e32 v25, v25
	v_mov_b32_e32 v178, v242
	v_fma_f32 v180,-v136,v176,v116
	v_fma_f32 v181,-v137,v176,v124
	v_fma_f32 v180, v180, v178, v134
	v_fma_f32 v181, v181, v178, v135
	v_cvt_f32_i32_e32 v24, v24
	v_mul_f32_e32 v116, 0xbfb8aa3b, v181
	v_exp_f32_e32 v161, v116
	v_fma_f32 v116,-v96,v176,v117
	v_fma_f32 v117, -v97, v176, v125
	v_cvt_f32_i32_e32 v17, v17
	v_fma_f32 v116, v116, v178, v100
	v_fma_f32 v117, v117, v178, v101
	v_add_f32_e32 v125, 1.0, v161
	v_mul_f32_e32 v124, 0xbfb8aa3b, v117
	v_exp_f32_e32 v124, v124
	v_rcp_f32_e32 v125, v125
	v_cvt_f32_i32_e32 v16, v16
	v_mul_f32_e32 v24, s20, v24
	v_mul_f32_e32 v25, s20, v25
	v_add_f32_e32 v124, 1.0, v124
	v_rcp_f32_e32 v124, v124
	v_mul_f32_e32 v125, v181, v125
	v_mul_f32_e32 v161, v180, v125
	v_mul_f32_e32 v117, v117, v124
	v_fma_f32 v124,-v132,v176,v118
	v_fma_f32 v125,-v133,v176,v126
	v_fma_f32 v124, v124, v178, v130
	v_fma_f32 v125, v125, v178, v131
	v_mul_f32_e32 v16, s24, v16
	v_mul_f32_e32 v17, s24, v17
	v_mul_f32_e32 v118, 0xbfb8aa3b, v125
	v_exp_f32_e32 v175, v118
	v_fma_f32 v118,-v98,v176,v119
	v_fma_f32 v119, -v99, v176, v127
	v_mul_f32_e32 v127, v116, v117
	v_fma_f32 v118, v118, v178, v102
	v_fma_f32 v119, v119, v178, v103
	v_add_f32_e32 v116, 1.0, v175
	v_mul_f32_e32 v126, 0xbfb8aa3b, v119
	v_exp_f32_e32 v126, v126
	v_rcp_f32_e32 v175, v116
	v_cvt_f32_i32_e32 v27, v27
	v_add_f32_e32 v116, 1.0, v126
	v_rcp_f32_e32 v126, v116
	v_fma_f32 v116,-v138,v176,v112
	v_fma_f32 v117,-v139,v176,v120
	v_mul_f32_e32 v120, v125, v175
	v_fma_f32 v116, v116, v178, v140
	v_fma_f32 v117, v117, v178, v141
	v_mul_f32_e32 v124, v124, v120
	v_mul_f32_e32 v112, 0xbfb8aa3b, v117
	v_exp_f32_e32 v112, v112
	v_mul_f32_e32 v119, v119, v126
	v_mul_f32_e32 v118, v118, v119
	v_add_f32_e32 v112, 1.0, v112
	v_rcp_f32_e32 v125, v112
	v_fma_f32 v112,-v84,v176,v113
	v_fma_f32 v113, -v85, v176, v121
	v_cvt_f32_i32_e32 v26, v26
	v_fma_f32 v112, v112, v178, v88
	v_fma_f32 v113, v113, v178, v89
	v_mul_f32_e32 v117, v117, v125
	v_mul_f32_e32 v120, 0xbfb8aa3b, v113
	v_exp_f32_e32 v120, v120
	v_mul_f32_e32 v119, v116, v117
	v_mov_b32_e32 v117, v122
	v_add_f32_e32 v116, 1.0, v120
	v_rcp_f32_e32 v120, v116
	v_fma_f32 v116,-v142,v176,v114
	v_fma_f32 v117, -v143, v176, v117
	v_cvt_f32_i32_e32 v19, v19
	v_fma_f32 v116, v116, v178, v162
	v_fma_f32 v117, v117, v178, v163
	v_mul_f32_e32 v113, v113, v120
	v_mul_f32_e32 v114, 0xbfb8aa3b, v117
	v_exp_f32_e32 v121, v114
	v_fma_f32 v114,-v86,v176,v115
	v_fma_f32 v115, -v87, v176, v123
	v_mul_f32_e32 v113, v112, v113
	v_fma_f32 v114, v114, v178, v90
	v_fma_f32 v115, v115, v178, v91
	v_add_f32_e32 v120, 1.0, v121
	v_mul_f32_e32 v122, 0xbfb8aa3b, v115
	v_exp_f32_e32 v122, v122
	v_rcp_f32_e32 v120, v120
	v_cvt_f32_i32_e32 v18, v18
	v_mul_f32_e32 v26, s20, v26
	v_mul_f32_e32 v27, s20, v27
	v_add_f32_e32 v121, 1.0, v122
	v_rcp_f32_e32 v121, v121
	v_mul_f32_e32 v112, v117, v120
	v_mul_f32_e32 v116, v116, v112
	v_med3_f32 v117, v127, s62, v173
	v_mul_f32_e32 v112, v115, v121
	v_mul_f32_e32 v114, v114, v112
	v_med3_f32 v115, v161, s62, v173
	v_cvt_pk_fp8_f32 v112, v115, v117
	v_med3_f32 v117, v118, s62, v173
	v_med3_f32 v118, v119, s62, v173
	v_med3_f32 v119, v113, s62, v173
	v_cvt_pk_fp8_f32 v113, v118, v119
	v_med3_f32 v115, v124, s62, v173
	v_cvt_pk_fp8_f32 v112, v115, v117 op_sel:[0,0,1]
	v_med3_f32 v115, v116, s62, v173
	v_med3_f32 v114, v114, s62, v173
	v_cvt_pk_fp8_f32 v113, v115, v114 op_sel:[0,0,1]
	v_mad_i64_i32 v[114:115], s[4:5], v174, s63, v[164:165]
	v_lshl_add_u64 v[114:115], v[114:115], 0, v[128:129]
	global_store_dwordx2 v[114:115], v[112:113], off
	v_or_b32_e32 v112, 32, v160
	v_ashrrev_i32_e32 v113, 31, v112
	v_lshl_add_u64 v[114:115], v[112:113], 3, s[14:15]
	v_mul_f32_e32 v18, s24, v18
	v_mul_f32_e32 v19, s24, v19
	v_cvt_f32_i32_e32 v13, v13
	v_cvt_f32_i32_e32 v12, v12
	v_cvt_f32_i32_e32 v5, v5
	v_cvt_f32_i32_e32 v4, v4
	v_cvt_f32_i32_e32 v15, v15
	v_mul_f32_e32 v12, s20, v12
	v_mul_f32_e32 v13, s20, v13
	v_cvt_f32_i32_e32 v14, v14
	v_mul_f32_e32 v4, s24, v4
	v_mul_f32_e32 v5, s24, v5
	v_cvt_f32_i32_e32 v7, v7
	v_cvt_f32_i32_e32 v6, v6
	v_mul_f32_e32 v14, s20, v14
	v_mul_f32_e32 v15, s20, v15
	v_cvt_f32_i32_e32 v9, v9
	v_cvt_f32_i32_e32 v8, v8
	v_mul_f32_e32 v6, s24, v6
	v_mul_f32_e32 v7, s24, v7
	v_cvt_f32_i32_e32 v1, v1
	v_cvt_f32_i32_e32 v0, v0
	v_mul_f32_e32 v8, s20, v8
	v_mul_f32_e32 v9, s20, v9
	v_cvt_f32_i32_e32 v11, v11
	v_cvt_f32_i32_e32 v10, v10
	v_mul_f32_e32 v0, s24, v0
	v_mul_f32_e32 v1, s24, v1
	v_cvt_f32_i32_e32 v3, v3
	v_cvt_f32_i32_e32 v2, v2
	v_mul_f32_e32 v10, s20, v10
; __device__ __forceinline__ u32x4 pack8bf(const f32x4 a, const f32x4 b) { u32x4 w; w.x = cvt_pk_bf16(a[0], a[1]); w.y = cvt_pk_bf16(a[2], a[3]); w.z = cvt_pk_bf16(b[0], b[1]); w.w = cvt_pk_bf16(b[2], b[3]); return w; }
;     __device__ __forceinline__ float qscale(const Unit& u) const { return ((u.pn >= 8 && u.pn <= 11) || u.pn == 17) ? 0.5f : 1.0f; }
; __device__ __forceinline__ void ln_stats(const float* st, int row, float& mu, float& rs) { const f32x2 s = *(const f32x2*)(st + 2 * (size_t)row); mu = s[0] * (1.0f / DM); rs = 1.0f / sqrtf(s[1] * (1.0f / DM) - mu * mu + LN_EPS); }
;     ...
;         if constexpr (QM == 2) { const float qs0_ = g.qs * E.qscale(cur), qs1_ = qs0_ * g.qs_b1; _Pragma("unroll") for (int a = 0; a < 2; ++a) _Pragma("unroll") for (int b = 0; b < 2; ++b) _Pragma("unroll") for (int m = 0; m < 4; ++m) _Pragma("unroll") for (int n = 0; n < 2; ++n) { const v4i t_ = __builtin_bit_cast(v4i, acc[a][b][m][n]); acc[a][b][m][n] = (f32x4){(float)t_[0], (float)t_[1], (float)t_[2], (float)t_[3]} * (b == 0 ? qs0_ : qs1_); } }
;     __device__ __forceinline__ void operator()(EPI_ARGS) const {
;     ...
;         for (int ai = 0; ai < 2; ++ai)
; #pragma unroll
;             for (int m = 0; m < 4; ++m) { const int row = row0 + ai * HALF + m * 16; f32x4 r[2];
;                 float mu = 0.f, rs = 1.f; if constexpr (FOLD) ln_stats(st, row, mu, rs);
; #pragma unroll
;                 for (int n = 0; n < 2; ++n) { f32x4 g = acc[ai][0][m][n], up = acc[ai][1][m][n];
;                     if constexpr (!PRE) { g = g * ascale; up = up * ascale; }
;                     if constexpr (FOLD) { g = (g - cg[n] * mu) * rs + dg[n]; up = (up - cu[n] * mu) * rs + du[n]; }
;                     if constexpr (!PRE) up = up * oscale;
; #pragma unroll
;                     for (int j = 0; j < 4; ++j) { const float e = __builtin_amdgcn_exp2f(g[j] * -1.4426950408889634f); r[n][j] = g[j] * __builtin_amdgcn_rcpf(1.0f + e) * up[j]; } }
;                 if constexpr (F8OUT) *(u32x2*)((unsigned char*)O + (size_t)row * ldc + col0) = pack8fp8(r[0], r[1]);
;                 else *(u32x4*)((bf16_t*)O + (size_t)row * ldc + col0) = pack8bf(r[0], r[1]); }
	v_mul_f32_e32 v11, s20, v11
	v_mul_f32_e32 v2, s24, v2
	v_mul_f32_e32 v3, s24, v3
	v_mul_f32_e32 v114,s26,v228
	v_mul_f32_e32 v115,s26,v229
	s_nop 0
	v_fma_f32 v113, -v114, v114, v115
	v_add_f32_e32 v113, 0x3727c5ac, v113
	v_rsq_f32_e32 v242, v113
	s_nop 1
	s_nop 0
	s_nop 0
	s_nop 1
	s_nop 1
	s_nop 0
	v_mov_b32_e32 v116, v242
	v_fma_f32 v118,-v136,v114,v92
	v_fma_f32 v119,-v137,v114,v108
	v_fma_f32 v118, v118, v116, v134
	v_fma_f32 v119, v119, v116, v135
	s_nop 0
	v_mul_f32_e32 v92, 0xbfb8aa3b, v119
	v_exp_f32_e32 v113, v92
	v_fma_f32 v92,-v96,v114,v93
	v_fma_f32 v93, -v97, v114, v109
	v_add_f32_e32 v109, 1.0, v113
	v_fma_f32 v92, v92, v116, v100
	v_fma_f32 v93, v93, v116, v101
	v_rcp_f32_e32 v109, v109
	v_mul_f32_e32 v108, 0xbfb8aa3b, v93
	v_exp_f32_e32 v108, v108
	v_mul_f32_e32 v109, v119, v109
	v_mul_f32_e32 v113, v118, v109
	v_add_f32_e32 v108, 1.0, v108
	v_rcp_f32_e32 v108, v108
	v_mov_b32_e32 v109, v110
	v_mul_f32_e32 v93, v93, v108
	v_fma_f32 v108,-v132,v114,v94
	v_fma_f32 v109, -v133, v114, v109
	s_nop 0
	v_fma_f32 v108, v108, v116, v130
	v_fma_f32 v109, v109, v116, v131
	s_nop 0
	v_mul_f32_e32 v94, 0xbfb8aa3b, v109
	v_exp_f32_e32 v117, v94
	v_fma_f32 v94,-v98,v114,v95
	v_fma_f32 v95, -v99, v114, v111
	v_mul_f32_e32 v111, v92, v93
	v_fma_f32 v94, v94, v116, v102
	v_fma_f32 v95, v95, v116, v103
	v_add_f32_e32 v92, 1.0, v117
	v_mul_f32_e32 v110, 0xbfb8aa3b, v95
	v_exp_f32_e32 v110, v110
	v_rcp_f32_e32 v117, v92
	v_add_f32_e32 v92, 1.0, v110
	v_rcp_f32_e32 v110, v92
	v_fma_f32 v92,-v138,v114,v80
	v_fma_f32 v93,-v139,v114,v104
	v_mul_f32_e32 v104, v109, v117
	v_fma_f32 v92, v92, v116, v140
	v_fma_f32 v93, v93, v116, v141
	v_mul_f32_e32 v108, v108, v104
	v_mul_f32_e32 v80, 0xbfb8aa3b, v93
	v_exp_f32_e32 v80, v80
	v_mul_f32_e32 v95, v95, v110
	v_mul_f32_e32 v94, v94, v95
	v_add_f32_e32 v80, 1.0, v80
	v_rcp_f32_e32 v109, v80
	v_fma_f32 v80,-v84,v114,v81
	v_fma_f32 v81, -v85, v114, v105
	v_mul_f32_e32 v93, v93, v109
	v_fma_f32 v80, v80, v116, v88
	v_fma_f32 v81, v81, v116, v89
	v_mul_f32_e32 v95, v92, v93
	v_mul_f32_e32 v104, 0xbfb8aa3b, v81
	v_exp_f32_e32 v104, v104
	v_mov_b32_e32 v93, v106
	v_add_f32_e32 v92, 1.0, v104
	v_rcp_f32_e32 v104, v92
	v_fma_f32 v92,-v142,v114,v82
	v_fma_f32 v93, -v143, v114, v93
	v_mul_f32_e32 v81, v81, v104
	v_fma_f32 v92, v92, v116, v162
	v_fma_f32 v93, v93, v116, v163
	v_mul_f32_e32 v81, v80, v81
	v_mul_f32_e32 v82, 0xbfb8aa3b, v93
	v_exp_f32_e32 v105, v82
	v_fma_f32 v82,-v86,v114,v83
	v_fma_f32 v83, -v87, v114, v107
	v_add_f32_e32 v104, 1.0, v105
	v_fma_f32 v82, v82, v116, v90
	v_fma_f32 v83, v83, v116, v91
	v_rcp_f32_e32 v104, v104
	v_mul_f32_e32 v106, 0xbfb8aa3b, v83
	v_exp_f32_e32 v106, v106
	v_mul_f32_e32 v80, v93, v104
	v_mul_f32_e32 v92, v92, v80
	v_add_f32_e32 v105, 1.0, v106
	v_rcp_f32_e32 v105, v105
	v_med3_f32 v93, v111, s62, v173
	v_mul_f32_e32 v80, v83, v105
	v_mul_f32_e32 v82, v82, v80
	v_med3_f32 v83, v113, s62, v173
	v_cvt_pk_fp8_f32 v80, v83, v93
	v_med3_f32 v93, v94, s62, v173
	v_med3_f32 v94, v95, s62, v173
	v_med3_f32 v95, v81, s62, v173
	v_cvt_pk_fp8_f32 v81, v94, v95
	v_med3_f32 v83, v108, s62, v173
	v_cvt_pk_fp8_f32 v80, v83, v93 op_sel:[0,0,1]
	v_med3_f32 v83, v92, s62, v173
	v_med3_f32 v82, v82, s62, v173
	v_cvt_pk_fp8_f32 v81, v83, v82 op_sel:[0,0,1]
	v_mad_i64_i32 v[82:83], s[4:5], v112, s63, v[164:165]
	v_lshl_add_u64 v[82:83], v[82:83], 0, v[128:129]
	global_store_dwordx2 v[82:83], v[80:81], off
	v_or_b32_e32 v80, 48, v160
	v_ashrrev_i32_e32 v81, 31, v80
	v_lshl_add_u64 v[82:83], v[80:81], 3, s[14:15]
	v_mul_f32_e32 v82,s26,v230
	v_mul_f32_e32 v83,s26,v231
	s_nop 0
	v_fma_f32 v81, -v82, v82, v83
	v_add_f32_e32 v81, 0x3727c5ac, v81
	v_rsq_f32_e32 v242, v81
	s_nop 1
	s_nop 0
	s_nop 0
	s_nop 1
	s_nop 1
	s_nop 0
	v_mov_b32_e32 v92, v242
	v_fma_f32 v94,-v136,v82,v68
	v_fma_f32 v95,-v137,v82,v76
	v_fma_f32 v94, v94, v92, v134
	v_fma_f32 v95, v95, v92, v135
	s_nop 0
	v_mul_f32_e32 v68, 0xbfb8aa3b, v95
	v_exp_f32_e32 v81, v68
	v_fma_f32 v68,-v96,v82,v69
	v_fma_f32 v69, -v97, v82, v77
	v_add_f32_e32 v77, 1.0, v81
	v_fma_f32 v68, v68, v92, v100
	v_fma_f32 v69, v69, v92, v101
	v_rcp_f32_e32 v77, v77
	v_mul_f32_e32 v76, 0xbfb8aa3b, v69
	v_exp_f32_e32 v76, v76
	v_mul_f32_e32 v77, v95, v77
	v_mul_f32_e32 v81, v94, v77
	v_add_f32_e32 v76, 1.0, v76
	v_rcp_f32_e32 v76, v76
	v_mov_b32_e32 v77, v78
	v_mul_f32_e32 v69, v69, v76
	v_fma_f32 v76,-v132,v82,v70
	v_fma_f32 v77, -v133, v82, v77
	s_nop 0
	v_fma_f32 v76, v76, v92, v130
	v_fma_f32 v77, v77, v92, v131
	s_nop 0
	v_mul_f32_e32 v70, 0xbfb8aa3b, v77
	v_exp_f32_e32 v93, v70
	v_fma_f32 v70,-v98,v82,v71
	v_fma_f32 v71, -v99, v82, v79
	v_mul_f32_e32 v79, v68, v69
	v_fma_f32 v70, v70, v92, v102
	v_fma_f32 v71, v71, v92, v103
	v_add_f32_e32 v68, 1.0, v93
	v_mul_f32_e32 v78, 0xbfb8aa3b, v71
	v_exp_f32_e32 v78, v78
	v_rcp_f32_e32 v93, v68
	v_add_f32_e32 v68, 1.0, v78
	v_rcp_f32_e32 v78, v68
	v_fma_f32 v68,-v138,v82,v64
	v_fma_f32 v69,-v139,v82,v72
	v_mul_f32_e32 v72, v77, v93
	v_fma_f32 v68, v68, v92, v140
	v_fma_f32 v69, v69, v92, v141
	v_mul_f32_e32 v76, v76, v72
	v_mul_f32_e32 v64, 0xbfb8aa3b, v69
	v_exp_f32_e32 v64, v64
	v_mul_f32_e32 v71, v71, v78
	v_mul_f32_e32 v70, v70, v71
	v_add_f32_e32 v64, 1.0, v64
	v_rcp_f32_e32 v77, v64
	v_fma_f32 v64,-v84,v82,v65
	v_fma_f32 v65, -v85, v82, v73
	v_mul_f32_e32 v69, v69, v77
	v_fma_f32 v64, v64, v92, v88
	v_fma_f32 v65, v65, v92, v89
	v_mul_f32_e32 v71, v68, v69
	v_mul_f32_e32 v72, 0xbfb8aa3b, v65
	v_exp_f32_e32 v72, v72
	v_mov_b32_e32 v69, v74
	v_add_f32_e32 v68, 1.0, v72
	v_rcp_f32_e32 v72, v68
	v_fma_f32 v68,-v142,v82,v66
	v_fma_f32 v69, -v143, v82, v69
	v_mul_f32_e32 v65, v65, v72
	v_fma_f32 v68, v68, v92, v162
; __device__ __forceinline__ u32x4 pack8bf(const f32x4 a, const f32x4 b) { u32x4 w; w.x = cvt_pk_bf16(a[0], a[1]); w.y = cvt_pk_bf16(a[2], a[3]); w.z = cvt_pk_bf16(b[0], b[1]); w.w = cvt_pk_bf16(b[2], b[3]); return w; }
;     __device__ __forceinline__ float qscale(const Unit& u) const { return ((u.pn >= 8 && u.pn <= 11) || u.pn == 17) ? 0.5f : 1.0f; }
; __device__ __forceinline__ void ln_stats(const float* st, int row, float& mu, float& rs) { const f32x2 s = *(const f32x2*)(st + 2 * (size_t)row); mu = s[0] * (1.0f / DM); rs = 1.0f / sqrtf(s[1] * (1.0f / DM) - mu * mu + LN_EPS); }
;     ...
;         if constexpr (QM == 2) { const float qs0_ = g.qs * E.qscale(cur), qs1_ = qs0_ * g.qs_b1; _Pragma("unroll") for (int a = 0; a < 2; ++a) _Pragma("unroll") for (int b = 0; b < 2; ++b) _Pragma("unroll") for (int m = 0; m < 4; ++m) _Pragma("unroll") for (int n = 0; n < 2; ++n) { const v4i t_ = __builtin_bit_cast(v4i, acc[a][b][m][n]); acc[a][b][m][n] = (f32x4){(float)t_[0], (float)t_[1], (float)t_[2], (float)t_[3]} * (b == 0 ? qs0_ : qs1_); } }
;     __device__ __forceinline__ void operator()(EPI_ARGS) const {
;     ...
;         for (int ai = 0; ai < 2; ++ai)
; #pragma unroll
;             for (int m = 0; m < 4; ++m) { const int row = row0 + ai * HALF + m * 16; f32x4 r[2];
;                 float mu = 0.f, rs = 1.f; if constexpr (FOLD) ln_stats(st, row, mu, rs);
; #pragma unroll
;                 for (int n = 0; n < 2; ++n) { f32x4 g = acc[ai][0][m][n], up = acc[ai][1][m][n];
;                     if constexpr (!PRE) { g = g * ascale; up = up * ascale; }
;                     if constexpr (FOLD) { g = (g - cg[n] * mu) * rs + dg[n]; up = (up - cu[n] * mu) * rs + du[n]; }
;                     if constexpr (!PRE) up = up * oscale;
; #pragma unroll
;                     for (int j = 0; j < 4; ++j) { const float e = __builtin_amdgcn_exp2f(g[j] * -1.4426950408889634f); r[n][j] = g[j] * __builtin_amdgcn_rcpf(1.0f + e) * up[j]; } }
;                 if constexpr (F8OUT) *(u32x2*)((unsigned char*)O + (size_t)row * ldc + col0) = pack8fp8(r[0], r[1]);
;                 else *(u32x4*)((bf16_t*)O + (size_t)row * ldc + col0) = pack8bf(r[0], r[1]); }
	v_fma_f32 v69, v69, v92, v163
	v_mul_f32_e32 v65, v64, v65
	v_mul_f32_e32 v66, 0xbfb8aa3b, v69
	v_exp_f32_e32 v73, v66
	v_fma_f32 v66,-v86,v82,v67
	v_fma_f32 v67, -v87, v82, v75
	v_add_f32_e32 v72, 1.0, v73
	v_fma_f32 v66, v66, v92, v90
	v_fma_f32 v67, v67, v92, v91
	v_rcp_f32_e32 v72, v72
	v_mul_f32_e32 v74, 0xbfb8aa3b, v67
	v_exp_f32_e32 v74, v74
	v_mul_f32_e32 v64, v69, v72
	v_mul_f32_e32 v68, v68, v64
	v_add_f32_e32 v73, 1.0, v74
	v_rcp_f32_e32 v73, v73
	v_med3_f32 v69, v79, s62, v173
	v_mul_f32_e32 v64, v67, v73
	v_mul_f32_e32 v66, v66, v64
	v_med3_f32 v67, v81, s62, v173
	v_cvt_pk_fp8_f32 v64, v67, v69
	v_med3_f32 v69, v70, s62, v173
	v_med3_f32 v70, v71, s62, v173
	v_med3_f32 v71, v65, s62, v173
	v_cvt_pk_fp8_f32 v65, v70, v71
	v_med3_f32 v67, v76, s62, v173
	v_cvt_pk_fp8_f32 v64, v67, v69 op_sel:[0,0,1]
	v_med3_f32 v67, v68, s62, v173
	v_med3_f32 v66, v66, s62, v173
	v_cvt_pk_fp8_f32 v65, v67, v66 op_sel:[0,0,1]
	v_mad_i64_i32 v[66:67], s[4:5], v80, s63, v[164:165]
	v_lshl_add_u64 v[66:67], v[66:67], 0, v[128:129]
	global_store_dwordx2 v[66:67], v[64:65], off
	v_add_u32_e32 v64, 0x80, v160
	v_ashrrev_i32_e32 v65, 31, v64
	v_lshl_add_u64 v[66:67], v[64:65], 3, s[14:15]
	v_mul_f32_e32 v66,s26,v232
	v_mul_f32_e32 v67,s26,v233
	s_nop 0
	v_fma_f32 v65, -v66, v66, v67
	v_add_f32_e32 v65, 0x3727c5ac, v65
	v_rsq_f32_e32 v242, v65
	s_nop 1
	s_nop 0
	s_nop 0
	s_nop 1
	s_nop 1
	s_nop 0
	v_mov_b32_e32 v68, v242
	v_fma_f32 v70,-v136,v66,v52
	v_fma_f32 v71,-v137,v66,v60
	v_fma_f32 v70, v70, v68, v134
	v_fma_f32 v71, v71, v68, v135
	s_nop 0
	v_mul_f32_e32 v52, 0xbfb8aa3b, v71
	v_exp_f32_e32 v65, v52
	v_fma_f32 v52,-v96,v66,v53
	v_fma_f32 v53, -v97, v66, v61
	v_add_f32_e32 v61, 1.0, v65
	v_fma_f32 v52, v52, v68, v100
	v_fma_f32 v53, v53, v68, v101
	v_rcp_f32_e32 v61, v61
	v_mul_f32_e32 v60, 0xbfb8aa3b, v53
	v_exp_f32_e32 v60, v60
	v_mul_f32_e32 v61, v71, v61
	v_mul_f32_e32 v65, v70, v61
	v_add_f32_e32 v60, 1.0, v60
	v_rcp_f32_e32 v60, v60
	v_mov_b32_e32 v61, v62
	v_mul_f32_e32 v53, v53, v60
	v_fma_f32 v60,-v132,v66,v54
	v_fma_f32 v61, -v133, v66, v61
	s_nop 0
	v_fma_f32 v60, v60, v68, v130
	v_fma_f32 v61, v61, v68, v131
	s_nop 0
	v_mul_f32_e32 v54, 0xbfb8aa3b, v61
	v_exp_f32_e32 v69, v54
	v_fma_f32 v54,-v98,v66,v55
	v_fma_f32 v55, -v99, v66, v63
	v_mul_f32_e32 v63, v52, v53
	v_fma_f32 v54, v54, v68, v102
	v_fma_f32 v55, v55, v68, v103
	v_add_f32_e32 v52, 1.0, v69
	v_mul_f32_e32 v62, 0xbfb8aa3b, v55
	v_exp_f32_e32 v62, v62
	v_rcp_f32_e32 v69, v52
	v_add_f32_e32 v52, 1.0, v62
	v_rcp_f32_e32 v62, v52
	v_fma_f32 v52,-v138,v66,v48
	v_fma_f32 v53,-v139,v66,v56
	v_mul_f32_e32 v56, v61, v69
	v_fma_f32 v52, v52, v68, v140
	v_fma_f32 v53, v53, v68, v141
	v_mul_f32_e32 v60, v60, v56
	v_mul_f32_e32 v48, 0xbfb8aa3b, v53
	v_exp_f32_e32 v48, v48
	v_mul_f32_e32 v55, v55, v62
	v_mul_f32_e32 v54, v54, v55
	v_add_f32_e32 v48, 1.0, v48
	v_rcp_f32_e32 v61, v48
	v_fma_f32 v48,-v84,v66,v49
	v_fma_f32 v49, -v85, v66, v57
	v_mul_f32_e32 v53, v53, v61
	v_fma_f32 v48, v48, v68, v88
	v_fma_f32 v49, v49, v68, v89
	v_mul_f32_e32 v55, v52, v53
	v_mul_f32_e32 v56, 0xbfb8aa3b, v49
	v_exp_f32_e32 v56, v56
	v_mov_b32_e32 v53, v58
	v_add_f32_e32 v52, 1.0, v56
	v_rcp_f32_e32 v56, v52
	v_fma_f32 v52,-v142,v66,v50
	v_fma_f32 v53, -v143, v66, v53
	v_mul_f32_e32 v49, v49, v56
	v_fma_f32 v52, v52, v68, v162
	v_fma_f32 v53, v53, v68, v163
	v_mul_f32_e32 v49, v48, v49
	v_mul_f32_e32 v50, 0xbfb8aa3b, v53
	v_exp_f32_e32 v57, v50
	v_fma_f32 v50,-v86,v66,v51
	v_fma_f32 v51, -v87, v66, v59
	v_add_f32_e32 v56, 1.0, v57
	v_fma_f32 v50, v50, v68, v90
	v_fma_f32 v51, v51, v68, v91
	v_rcp_f32_e32 v56, v56
	v_mul_f32_e32 v58, 0xbfb8aa3b, v51
	v_exp_f32_e32 v58, v58
	v_mul_f32_e32 v48, v53, v56
	v_mul_f32_e32 v52, v52, v48
	v_add_f32_e32 v57, 1.0, v58
	v_rcp_f32_e32 v57, v57
	v_med3_f32 v53, v63, s62, v173
	v_mul_f32_e32 v48, v51, v57
	v_mul_f32_e32 v50, v50, v48
	v_med3_f32 v51, v65, s62, v173
	v_cvt_pk_fp8_f32 v48, v51, v53
	v_med3_f32 v53, v54, s62, v173
	v_med3_f32 v54, v55, s62, v173
	v_med3_f32 v55, v49, s62, v173
	v_cvt_pk_fp8_f32 v49, v54, v55
	v_med3_f32 v51, v60, s62, v173
	v_cvt_pk_fp8_f32 v48, v51, v53 op_sel:[0,0,1]
	v_med3_f32 v51, v52, s62, v173
	v_med3_f32 v50, v50, s62, v173
	v_cvt_pk_fp8_f32 v49, v51, v50 op_sel:[0,0,1]
	v_mad_i64_i32 v[50:51], s[4:5], v64, s63, v[164:165]
	v_lshl_add_u64 v[50:51], v[50:51], 0, v[128:129]
	global_store_dwordx2 v[50:51], v[48:49], off
	v_add_u32_e32 v48, 0x90, v160
	v_ashrrev_i32_e32 v49, 31, v48
	v_lshl_add_u64 v[50:51], v[48:49], 3, s[14:15]
	v_mul_f32_e32 v50,s26,v234
	v_mul_f32_e32 v51,s26,v235
	s_nop 0
	v_fma_f32 v49, -v50, v50, v51
	v_add_f32_e32 v49, 0x3727c5ac, v49
	v_rsq_f32_e32 v242, v49
	s_nop 1
	s_nop 0
	s_nop 0
	s_nop 1
	s_nop 1
	s_nop 0
	v_mov_b32_e32 v52, v242
	v_fma_f32 v54,-v136,v50,v36
	v_fma_f32 v55,-v137,v50,v44
	v_fma_f32 v54, v54, v52, v134
	v_fma_f32 v55, v55, v52, v135
	s_nop 0
	v_mul_f32_e32 v36, 0xbfb8aa3b, v55
	v_exp_f32_e32 v49, v36
	v_fma_f32 v36,-v96,v50,v37
	v_fma_f32 v37, -v97, v50, v45
	v_add_f32_e32 v45, 1.0, v49
	v_fma_f32 v36, v36, v52, v100
	v_fma_f32 v37, v37, v52, v101
	v_rcp_f32_e32 v45, v45
	v_mul_f32_e32 v44, 0xbfb8aa3b, v37
	v_exp_f32_e32 v44, v44
	v_mul_f32_e32 v45, v55, v45
	v_mul_f32_e32 v49, v54, v45
	v_add_f32_e32 v44, 1.0, v44
	v_rcp_f32_e32 v44, v44
	v_mov_b32_e32 v45, v46
	v_mul_f32_e32 v37, v37, v44
	v_fma_f32 v44,-v132,v50,v38
	v_fma_f32 v45, -v133, v50, v45
	s_nop 0
	v_fma_f32 v44, v44, v52, v130
	v_fma_f32 v45, v45, v52, v131
	s_nop 0
	v_mul_f32_e32 v38, 0xbfb8aa3b, v45
	v_exp_f32_e32 v53, v38
	v_fma_f32 v38,-v98,v50,v39
	v_fma_f32 v39, -v99, v50, v47
	v_mul_f32_e32 v47, v36, v37
; __device__ __forceinline__ u32x4 pack8bf(const f32x4 a, const f32x4 b) { u32x4 w; w.x = cvt_pk_bf16(a[0], a[1]); w.y = cvt_pk_bf16(a[2], a[3]); w.z = cvt_pk_bf16(b[0], b[1]); w.w = cvt_pk_bf16(b[2], b[3]); return w; }
;     __device__ __forceinline__ float qscale(const Unit& u) const { return ((u.pn >= 8 && u.pn <= 11) || u.pn == 17) ? 0.5f : 1.0f; }
; __device__ __forceinline__ void ln_stats(const float* st, int row, float& mu, float& rs) { const f32x2 s = *(const f32x2*)(st + 2 * (size_t)row); mu = s[0] * (1.0f / DM); rs = 1.0f / sqrtf(s[1] * (1.0f / DM) - mu * mu + LN_EPS); }
;     ...
;         if constexpr (QM == 2) { const float qs0_ = g.qs * E.qscale(cur), qs1_ = qs0_ * g.qs_b1; _Pragma("unroll") for (int a = 0; a < 2; ++a) _Pragma("unroll") for (int b = 0; b < 2; ++b) _Pragma("unroll") for (int m = 0; m < 4; ++m) _Pragma("unroll") for (int n = 0; n < 2; ++n) { const v4i t_ = __builtin_bit_cast(v4i, acc[a][b][m][n]); acc[a][b][m][n] = (f32x4){(float)t_[0], (float)t_[1], (float)t_[2], (float)t_[3]} * (b == 0 ? qs0_ : qs1_); } }
;     __device__ __forceinline__ void operator()(EPI_ARGS) const {
;     ...
;         for (int ai = 0; ai < 2; ++ai)
; #pragma unroll
;             for (int m = 0; m < 4; ++m) { const int row = row0 + ai * HALF + m * 16; f32x4 r[2];
;                 float mu = 0.f, rs = 1.f; if constexpr (FOLD) ln_stats(st, row, mu, rs);
; #pragma unroll
;                 for (int n = 0; n < 2; ++n) { f32x4 g = acc[ai][0][m][n], up = acc[ai][1][m][n];
;                     if constexpr (!PRE) { g = g * ascale; up = up * ascale; }
;                     if constexpr (FOLD) { g = (g - cg[n] * mu) * rs + dg[n]; up = (up - cu[n] * mu) * rs + du[n]; }
;                     if constexpr (!PRE) up = up * oscale;
; #pragma unroll
;                     for (int j = 0; j < 4; ++j) { const float e = __builtin_amdgcn_exp2f(g[j] * -1.4426950408889634f); r[n][j] = g[j] * __builtin_amdgcn_rcpf(1.0f + e) * up[j]; } }
;                 if constexpr (F8OUT) *(u32x2*)((unsigned char*)O + (size_t)row * ldc + col0) = pack8fp8(r[0], r[1]);
;                 else *(u32x4*)((bf16_t*)O + (size_t)row * ldc + col0) = pack8bf(r[0], r[1]); }
	v_fma_f32 v38, v38, v52, v102
	v_fma_f32 v39, v39, v52, v103
	v_add_f32_e32 v36, 1.0, v53
	v_mul_f32_e32 v46, 0xbfb8aa3b, v39
	v_exp_f32_e32 v46, v46
	v_rcp_f32_e32 v53, v36
	v_add_f32_e32 v36, 1.0, v46
	v_rcp_f32_e32 v46, v36
	v_fma_f32 v36,-v138,v50,v32
	v_fma_f32 v37,-v139,v50,v40
	v_mul_f32_e32 v40, v45, v53
	v_fma_f32 v36, v36, v52, v140
	v_fma_f32 v37, v37, v52, v141
	v_mul_f32_e32 v44, v44, v40
	v_mul_f32_e32 v32, 0xbfb8aa3b, v37
	v_exp_f32_e32 v32, v32
	v_mul_f32_e32 v39, v39, v46
	v_mul_f32_e32 v38, v38, v39
	v_add_f32_e32 v32, 1.0, v32
	v_rcp_f32_e32 v45, v32
	v_fma_f32 v32,-v84,v50,v33
	v_fma_f32 v33, -v85, v50, v41
	v_mul_f32_e32 v37, v37, v45
	v_fma_f32 v32, v32, v52, v88
	v_fma_f32 v33, v33, v52, v89
	v_mul_f32_e32 v39, v36, v37
	v_mul_f32_e32 v40, 0xbfb8aa3b, v33
	v_exp_f32_e32 v40, v40
	v_mov_b32_e32 v37, v42
	v_add_f32_e32 v36, 1.0, v40
	v_rcp_f32_e32 v40, v36
	v_fma_f32 v36,-v142,v50,v34
	v_fma_f32 v37, -v143, v50, v37
	v_mul_f32_e32 v33, v33, v40
	v_fma_f32 v36, v36, v52, v162
	v_fma_f32 v37, v37, v52, v163
	v_mul_f32_e32 v33, v32, v33
	v_mul_f32_e32 v34, 0xbfb8aa3b, v37
	v_exp_f32_e32 v41, v34
	v_fma_f32 v34,-v86,v50,v35
	v_fma_f32 v35, -v87, v50, v43
	v_add_f32_e32 v40, 1.0, v41
	v_fma_f32 v34, v34, v52, v90
	v_fma_f32 v35, v35, v52, v91
	v_rcp_f32_e32 v40, v40
	v_mul_f32_e32 v42, 0xbfb8aa3b, v35
	v_exp_f32_e32 v42, v42
	v_mul_f32_e32 v32, v37, v40
	v_mul_f32_e32 v36, v36, v32
	v_add_f32_e32 v41, 1.0, v42
	v_rcp_f32_e32 v41, v41
	v_med3_f32 v37, v47, s62, v173
	v_mul_f32_e32 v32, v35, v41
	v_mul_f32_e32 v34, v34, v32
	v_med3_f32 v35, v49, s62, v173
	v_cvt_pk_fp8_f32 v32, v35, v37
	v_med3_f32 v37, v38, s62, v173
	v_med3_f32 v38, v39, s62, v173
	v_med3_f32 v39, v33, s62, v173
	v_cvt_pk_fp8_f32 v33, v38, v39
	v_med3_f32 v35, v44, s62, v173
	v_cvt_pk_fp8_f32 v32, v35, v37 op_sel:[0,0,1]
	v_med3_f32 v35, v36, s62, v173
	v_med3_f32 v34, v34, s62, v173
	v_cvt_pk_fp8_f32 v33, v35, v34 op_sel:[0,0,1]
	v_mad_i64_i32 v[34:35], s[4:5], v48, s63, v[164:165]
	v_lshl_add_u64 v[34:35], v[34:35], 0, v[128:129]
	global_store_dwordx2 v[34:35], v[32:33], off
	v_add_u32_e32 v32, 0xa0, v160
	v_ashrrev_i32_e32 v33, 31, v32
	v_lshl_add_u64 v[34:35], v[32:33], 3, s[14:15]
	v_mul_f32_e32 v34,s26,v236
	v_mul_f32_e32 v35,s26,v237
	s_nop 0
	v_fma_f32 v33, -v34, v34, v35
	v_add_f32_e32 v33, 0x3727c5ac, v33
	v_rsq_f32_e32 v242, v33
	s_nop 1
	s_nop 0
	s_nop 0
	s_nop 1
	s_nop 1
	s_nop 0
	v_mov_b32_e32 v36, v242
	v_fma_f32 v38,-v136,v34,v20
	v_fma_f32 v39,-v137,v34,v28
	v_fma_f32 v38, v38, v36, v134
	v_fma_f32 v39, v39, v36, v135
	s_nop 0
	v_mul_f32_e32 v20, 0xbfb8aa3b, v39
	v_exp_f32_e32 v33, v20
	v_fma_f32 v20,-v96,v34,v21
	v_fma_f32 v21, -v97, v34, v29
	v_add_f32_e32 v29, 1.0, v33
	v_fma_f32 v20, v20, v36, v100
	v_fma_f32 v21, v21, v36, v101
	v_rcp_f32_e32 v29, v29
	v_mul_f32_e32 v28, 0xbfb8aa3b, v21
	v_exp_f32_e32 v28, v28
	v_mul_f32_e32 v29, v39, v29
	v_mul_f32_e32 v33, v38, v29
	v_add_f32_e32 v28, 1.0, v28
	v_rcp_f32_e32 v28, v28
	v_mov_b32_e32 v29, v30
	v_mul_f32_e32 v21, v21, v28
	v_fma_f32 v28,-v132,v34,v22
	v_fma_f32 v29, -v133, v34, v29
	s_nop 0
	v_fma_f32 v28, v28, v36, v130
	v_fma_f32 v29, v29, v36, v131
	s_nop 0
	v_mul_f32_e32 v22, 0xbfb8aa3b, v29
	v_exp_f32_e32 v37, v22
	v_fma_f32 v22,-v98,v34,v23
	v_fma_f32 v23, -v99, v34, v31
	v_mul_f32_e32 v31, v20, v21
	v_fma_f32 v22, v22, v36, v102
	v_fma_f32 v23, v23, v36, v103
	v_add_f32_e32 v20, 1.0, v37
	v_mul_f32_e32 v30, 0xbfb8aa3b, v23
	v_exp_f32_e32 v30, v30
	v_rcp_f32_e32 v37, v20
	v_add_f32_e32 v20, 1.0, v30
	v_rcp_f32_e32 v30, v20
	v_fma_f32 v20,-v138,v34,v16
	v_fma_f32 v21,-v139,v34,v24
	v_mul_f32_e32 v24, v29, v37
	v_fma_f32 v20, v20, v36, v140
	v_fma_f32 v21, v21, v36, v141
	v_mul_f32_e32 v28, v28, v24
	v_mul_f32_e32 v16, 0xbfb8aa3b, v21
	v_exp_f32_e32 v16, v16
	v_mul_f32_e32 v23, v23, v30
	v_mul_f32_e32 v22, v22, v23
	v_add_f32_e32 v16, 1.0, v16
	v_rcp_f32_e32 v29, v16
	v_fma_f32 v16,-v84,v34,v17
	v_fma_f32 v17, -v85, v34, v25
	v_mul_f32_e32 v21, v21, v29
	v_fma_f32 v16, v16, v36, v88
	v_fma_f32 v17, v17, v36, v89
	v_mul_f32_e32 v23, v20, v21
	v_mul_f32_e32 v24, 0xbfb8aa3b, v17
	v_exp_f32_e32 v24, v24
	v_mov_b32_e32 v21, v26
	v_add_f32_e32 v20, 1.0, v24
	v_rcp_f32_e32 v24, v20
	v_fma_f32 v20,-v142,v34,v18
	v_fma_f32 v21, -v143, v34, v21
	v_mul_f32_e32 v17, v17, v24
	v_fma_f32 v20, v20, v36, v162
	v_fma_f32 v21, v21, v36, v163
; __device__ __forceinline__ u32x4 pack8bf(const f32x4 a, const f32x4 b) { u32x4 w; w.x = cvt_pk_bf16(a[0], a[1]); w.y = cvt_pk_bf16(a[2], a[3]); w.z = cvt_pk_bf16(b[0], b[1]); w.w = cvt_pk_bf16(b[2], b[3]); return w; }
;     __device__ __forceinline__ float qscale(const Unit& u) const { return ((u.pn >= 8 && u.pn <= 11) || u.pn == 17) ? 0.5f : 1.0f; }
; __device__ __forceinline__ void ln_stats(const float* st, int row, float& mu, float& rs) { const f32x2 s = *(const f32x2*)(st + 2 * (size_t)row); mu = s[0] * (1.0f / DM); rs = 1.0f / sqrtf(s[1] * (1.0f / DM) - mu * mu + LN_EPS); }
;     ...
;         if constexpr (QM == 2) { const float qs0_ = g.qs * E.qscale(cur), qs1_ = qs0_ * g.qs_b1; _Pragma("unroll") for (int a = 0; a < 2; ++a) _Pragma("unroll") for (int b = 0; b < 2; ++b) _Pragma("unroll") for (int m = 0; m < 4; ++m) _Pragma("unroll") for (int n = 0; n < 2; ++n) { const v4i t_ = __builtin_bit_cast(v4i, acc[a][b][m][n]); acc[a][b][m][n] = (f32x4){(float)t_[0], (float)t_[1], (float)t_[2], (float)t_[3]} * (b == 0 ? qs0_ : qs1_); } }
;     __device__ __forceinline__ void operator()(EPI_ARGS) const {
;     ...
;         for (int ai = 0; ai < 2; ++ai)
; #pragma unroll
;             for (int m = 0; m < 4; ++m) { const int row = row0 + ai * HALF + m * 16; f32x4 r[2];
;                 float mu = 0.f, rs = 1.f; if constexpr (FOLD) ln_stats(st, row, mu, rs);
; #pragma unroll
;                 for (int n = 0; n < 2; ++n) { f32x4 g = acc[ai][0][m][n], up = acc[ai][1][m][n];
;                     if constexpr (!PRE) { g = g * ascale; up = up * ascale; }
;                     if constexpr (FOLD) { g = (g - cg[n] * mu) * rs + dg[n]; up = (up - cu[n] * mu) * rs + du[n]; }
;                     if constexpr (!PRE) up = up * oscale;
; #pragma unroll
;                     for (int j = 0; j < 4; ++j) { const float e = __builtin_amdgcn_exp2f(g[j] * -1.4426950408889634f); r[n][j] = g[j] * __builtin_amdgcn_rcpf(1.0f + e) * up[j]; } }
;                 if constexpr (F8OUT) *(u32x2*)((unsigned char*)O + (size_t)row * ldc + col0) = pack8fp8(r[0], r[1]);
;                 else *(u32x4*)((bf16_t*)O + (size_t)row * ldc + col0) = pack8bf(r[0], r[1]); }
	v_mul_f32_e32 v17, v16, v17
	v_mul_f32_e32 v18, 0xbfb8aa3b, v21
	v_exp_f32_e32 v25, v18
	v_fma_f32 v18,-v86,v34,v19
	v_fma_f32 v19, -v87, v34, v27
	v_add_f32_e32 v24, 1.0, v25
	v_fma_f32 v18, v18, v36, v90
	v_fma_f32 v19, v19, v36, v91
	v_rcp_f32_e32 v24, v24
	v_mul_f32_e32 v26, 0xbfb8aa3b, v19
	v_exp_f32_e32 v26, v26
	v_mul_f32_e32 v16, v21, v24
	v_mul_f32_e32 v20, v20, v16
	v_add_f32_e32 v25, 1.0, v26
	v_rcp_f32_e32 v25, v25
	v_med3_f32 v21, v31, s62, v173
	v_mul_f32_e32 v16, v19, v25
	v_mul_f32_e32 v18, v18, v16
	v_med3_f32 v19, v33, s62, v173
	v_cvt_pk_fp8_f32 v16, v19, v21
	v_med3_f32 v21, v22, s62, v173
	v_med3_f32 v22, v23, s62, v173
	v_med3_f32 v23, v17, s62, v173
	v_cvt_pk_fp8_f32 v17, v22, v23
	v_med3_f32 v19, v28, s62, v173
	v_cvt_pk_fp8_f32 v16, v19, v21 op_sel:[0,0,1]
	v_med3_f32 v19, v20, s62, v173
	v_med3_f32 v18, v18, s62, v173
	v_cvt_pk_fp8_f32 v17, v19, v18 op_sel:[0,0,1]
	v_mad_i64_i32 v[18:19], s[4:5], v32, s63, v[164:165]
	v_lshl_add_u64 v[18:19], v[18:19], 0, v[128:129]
	global_store_dwordx2 v[18:19], v[16:17], off
	v_add_u32_e32 v16, 0xb0, v160
	v_ashrrev_i32_e32 v17, 31, v16
	v_lshl_add_u64 v[18:19], v[16:17], 3, s[14:15]
	v_mul_f32_e32 v18,s26,v238
	v_mul_f32_e32 v19,s26,v239
	s_nop 0
	v_fma_f32 v17, -v18, v18, v19
	v_add_f32_e32 v17, 0x3727c5ac, v17
	v_rsq_f32_e32 v242, v17
	s_nop 1
	s_nop 0
	s_nop 0
	s_nop 1
	s_nop 1
	s_nop 0
	v_mov_b32_e32 v20, v242
	v_fma_f32 v22,-v136,v18,v4
	v_fma_f32 v23,-v137,v18,v12
	v_fma_f32 v22, v22, v20, v134
	v_fma_f32 v23, v23, v20, v135
	s_andn2_b64 vcc, exec, s[2:3]
	v_mul_f32_e32 v4, 0xbfb8aa3b, v23
	v_exp_f32_e32 v17, v4
	v_fma_f32 v4,-v96,v18,v5
	v_fma_f32 v5, -v97, v18, v13
	s_mov_b64 s[2:3], -1
	v_fma_f32 v4, v4, v20, v100
	v_fma_f32 v5, v5, v20, v101
	v_add_f32_e32 v13, 1.0, v17
	v_mul_f32_e32 v12, 0xbfb8aa3b, v5
	v_exp_f32_e32 v12, v12
	v_rcp_f32_e32 v13, v13
	v_add_f32_e32 v12, 1.0, v12
	v_rcp_f32_e32 v12, v12
	v_mul_f32_e32 v13, v23, v13
	v_mul_f32_e32 v17, v22, v13
	v_mul_f32_e32 v5, v5, v12
	v_fma_f32 v12,-v132,v18,v6
	v_fma_f32 v13,-v133,v18,v14
	v_fma_f32 v12, v12, v20, v130
	v_fma_f32 v13, v13, v20, v131
	s_nop 0
	v_mul_f32_e32 v6, 0xbfb8aa3b, v13
	v_exp_f32_e32 v21, v6
	v_fma_f32 v6,-v98,v18,v7
	v_fma_f32 v7, -v99, v18, v15
	v_mul_f32_e32 v15, v4, v5
	v_fma_f32 v6, v6, v20, v102
	v_fma_f32 v7, v7, v20, v103
	v_add_f32_e32 v4, 1.0, v21
	v_mul_f32_e32 v14, 0xbfb8aa3b, v7
	v_exp_f32_e32 v14, v14
	v_rcp_f32_e32 v21, v4
	v_add_f32_e32 v4, 1.0, v14
	v_rcp_f32_e32 v14, v4
	v_fma_f32 v4,-v138,v18,v0
	v_fma_f32 v5,-v139,v18,v8
	v_mul_f32_e32 v8, v13, v21
	v_fma_f32 v4, v4, v20, v140
	v_fma_f32 v5, v5, v20, v141
	v_mul_f32_e32 v12, v12, v8
	v_mul_f32_e32 v0, 0xbfb8aa3b, v5
	v_exp_f32_e32 v0, v0
	v_mul_f32_e32 v7, v7, v14
	v_mul_f32_e32 v6, v6, v7
	v_add_f32_e32 v0, 1.0, v0
	v_rcp_f32_e32 v13, v0
	v_fma_f32 v0,-v84,v18,v1
	v_fma_f32 v1, -v85, v18, v9
	v_mul_f32_e32 v5, v5, v13
	v_fma_f32 v0, v0, v20, v88
	v_fma_f32 v1, v1, v20, v89
	v_mul_f32_e32 v7, v4, v5
	v_mul_f32_e32 v8, 0xbfb8aa3b, v1
	v_exp_f32_e32 v8, v8
	v_mov_b32_e32 v5, v10
	v_add_f32_e32 v4, 1.0, v8
	v_rcp_f32_e32 v8, v4
	v_fma_f32 v4,-v142,v18,v2
	v_fma_f32 v5, -v143, v18, v5
	v_mul_f32_e32 v1, v1, v8
	v_fma_f32 v4, v4, v20, v162
	v_fma_f32 v5, v5, v20, v163
	v_mul_f32_e32 v1, v0, v1
	v_mul_f32_e32 v2, 0xbfb8aa3b, v5
	v_exp_f32_e32 v9, v2
	v_fma_f32 v2,-v86,v18,v3
	v_fma_f32 v3, -v87, v18, v11
	v_add_f32_e32 v8, 1.0, v9
	v_fma_f32 v2, v2, v20, v90
	v_fma_f32 v3, v3, v20, v91
	v_rcp_f32_e32 v8, v8
	v_mul_f32_e32 v10, 0xbfb8aa3b, v3
	v_exp_f32_e32 v10, v10
	v_mul_f32_e32 v0, v5, v8
	v_mul_f32_e32 v4, v4, v0
	v_add_f32_e32 v9, 1.0, v10
	v_rcp_f32_e32 v9, v9
	v_med3_f32 v5, v15, s62, v173
	v_mul_f32_e32 v0, v3, v9
	v_mul_f32_e32 v2, v2, v0
	v_med3_f32 v3, v17, s62, v173
	v_cvt_pk_fp8_f32 v0, v3, v5
	v_med3_f32 v5, v6, s62, v173
	v_med3_f32 v6, v7, s62, v173
	v_med3_f32 v7, v1, s62, v173
	v_cvt_pk_fp8_f32 v1, v6, v7
	v_med3_f32 v3, v12, s62, v173
	v_cvt_pk_fp8_f32 v0, v3, v5 op_sel:[0,0,1]
	v_med3_f32 v3, v4, s62, v173
	v_med3_f32 v2, v2, s62, v173
	v_cvt_pk_fp8_f32 v1, v3, v2 op_sel:[0,0,1]
	v_mad_i64_i32 v[2:3], s[4:5], v16, s63, v[164:165]
	v_lshl_add_u64 v[2:3], v[2:3], 0, v[128:129]
	global_store_dwordx2 v[2:3], v[0:1], off
	s_cbranch_vccnz .LBB0_3772
	s_andn2_b64 vcc, exec, s[6:7]
	s_cbranch_vccnz .LBB0_3771
	s_barrier
	s_branch .LBB0_3771
